# attention key-tile loops (stick-breaking and sliding-window): K tile prefetched one iteration ahead instead of loaded at its use
# baseline (speedup 1.0000x reference)
; DEVINL void swa_task(const Ctx& c, int layer, int b, int qh, int qg) {
;     ...
;     const bf16_t* zb = c.Z() + (size_t)b * L * ZW;
;     bf16x8 qf[4];
;     {
;         const bf16_t* qp = zb + (size_t)(q0 + r) * ZW + Z_DQ + qh * 64 + 8 * h;
; #pragma unroll
;         for (int s = 0; s < 4; ++s) qf[s] = *(const bf16x8*)(qp + 16 * s);
;     }
;     f32x16 o[2];
; #pragma unroll
;     for (int d = 0; d < 2; ++d)
; #pragma unroll
;         for (int i = 0; i < 16; ++i) o[d][i] = 0.f;
;     const float slope2 = fexp2(-(float)(qh + 1)) * LOG2E;
;     float mrun = c.in[I_SINK][layer * 8 + qh] * LOG2E, lrun = 1.f;
;     const int qpos = q0 + r;
;     const bf16_t* vtb = c.DVT() + (size_t)(b * 128 + kvh * 64 + r) * L + 4 * h;
;     const int kt_lo = (qg - 4) > 4 ? (qg - 4) : 4;
;     const int ntiles = 1 + (qg >= 4 ? (qg - kt_lo + 1) : 0);
;     bf16x8 kfn[4], vfn[2][2];
;     ...
;     SWA_LOAD(3);
;     for (int it = 0; it < ntiles; ++it) {
;         const bool meta = (it == 0);
;         const int kt = meta ? 3 : (kt_lo + it - 1);
;         const int k0 = kt * 32;
;         bf16x8 kf[4], vf[2][2];
; #pragma unroll
;         for (int s = 0; s < 4; ++s) kf[s] = kfn[s];
; #pragma unroll
;         for (int d = 0; d < 2; ++d)
; #pragma unroll
;             for (int s = 0; s < 2; ++s) vf[d][s] = vfn[d][s];
;         { const int nk = (it + 1 < ntiles) ? (kt_lo + it) : kt; SWA_LOAD(nk); }
;         f32x16 st;
; #pragma unroll
;         for (int i = 0; i < 16; ++i) st[i] = 0.f;
; #pragma unroll
;         for (int s = 0; s < 4; ++s) st = MFMA32(kf[s], qf[s], st);
;         float sc[16]; float tmax = -INFINITY;
; #pragma unroll
;         for (int i = 0; i < 16; ++i) {
;             const int key = k0 + (i & 3) + 8 * (i >> 2) + 4 * h;
;             const int dist = qpos - key;
;             const bool ok = meta ? (key >= 112 && dist >= 0) : (dist >= 0 && dist < 128);
;             const float v = meta ? st[i] : st[i] - slope2 * (float)dist;
;             sc[i] = ok ? v : -INFINITY;
;             tmax = fmaxf(tmax, sc[i]);
;         }
;         tmax = fmaxf(tmax, __shfl_xor(tmax, 32));
; DEVINL void phase_mixers(const Ctx& c, int layer, unsigned char* lds) {
;     ...
;             if (i < NSB) { const int qg = 67 - i / 64, bh = i & 63; sb_task(c, bh >> 3, bh & 7, qg); }
;             else { const int i2 = i - NSB; const int qg = 67 - i2 / 64, bh = i2 & 63; swa_task(c, layer, bh >> 3, bh & 7, qg); }
.LBB0_244:
	s_movk_i32 s0, 0x10ff
	v_cmp_lt_i32_e32 vcc, s0, v168
	v_bfe_u32 v33, v168, 3, 3
	s_and_saveexec_b64 s[0:1], vcc
	s_xor_b64 s[0:1], exec, s[0:1]
	s_cbranch_execz .LBB0_256
	v_add_u32_e32 v1, 0xffffef00, v168
	v_lshrrev_b32_e32 v0, 6, v1
	v_sub_u32_e32 v0, 0x43, v0
	v_mov_b32_e32 v2, v160
	v_lshlrev_b32_e32 v34, 5, v0
	s_movk_i32 s4, 0x880
	v_and_b32_e32 v101, 31, v2
	v_bfe_u32 v40, v2, 5, 1
	v_mad_u32_u24 v2, v33, s4, v34
	v_or_b32_e32 v2, v101, v2
	v_lshlrev_b32_e32 v64, 10, v2
	s_movk_i32 s4, 0x1040
	v_lshl_add_u64 v[88:89], v[82:83], 0, v[64:65]
	v_cmp_gt_u32_e32 vcc, s4, v1
	v_lshlrev_b32_e32 v90, 2, v40
	s_and_saveexec_b64 s[4:5], vcc
	s_xor_b64 s[4:5], exec, s[4:5]
	s_cbranch_execz .LBB0_253
	v_max_u32_e32 v42, 8, v0
	v_sub_u32_e32 v41, v0, v42
	v_mov_b32_e32 v91, v65
	v_cmp_lt_i32_e32 vcc, -6, v41
	v_mov_b32_e32 v16, 0
	v_mov_b32_e32 v32, 1.0
	v_lshlrev_b32_e32 v92, 1, v90
	v_mov_b32_e32 v17, 0
	v_mov_b32_e32 v18, 0
	v_mov_b32_e32 v19, 0
	v_mov_b32_e32 v20, 0
	v_mov_b32_e32 v21, 0
	v_mov_b32_e32 v22, 0
	v_mov_b32_e32 v23, 0
	v_mov_b32_e32 v24, 0
	v_mov_b32_e32 v25, 0
	v_mov_b32_e32 v26, 0
	v_mov_b32_e32 v27, 0
	v_mov_b32_e32 v28, 0
	v_mov_b32_e32 v29, 0
	v_mov_b32_e32 v30, 0
	v_mov_b32_e32 v31, 0
	v_mov_b32_e32 v0, 0
	v_mov_b32_e32 v1, 0
	v_mov_b32_e32 v2, 0
	v_mov_b32_e32 v3, 0
	v_mov_b32_e32 v4, 0
	v_mov_b32_e32 v5, 0
	v_mov_b32_e32 v6, 0
	v_mov_b32_e32 v7, 0
	v_mov_b32_e32 v8, 0
	v_mov_b32_e32 v9, 0
	v_mov_b32_e32 v10, 0
	v_mov_b32_e32 v11, 0
	v_mov_b32_e32 v12, 0
	v_mov_b32_e32 v13, 0
	v_mov_b32_e32 v14, 0
	v_mov_b32_e32 v15, 0
	s_and_saveexec_b64 s[6:7], vcc
	s_cbranch_execz .LBB0_252
	v_lshlrev_b32_e32 v1, 4, v168
	v_lshlrev_b32_e32 v0, 7, v33
	v_and_b32_e32 v2, 64, v1
	s_mov_b32 s8, 0x2420000
	v_or3_b32 v0, v0, v2, v101
	v_mul_lo_u32 v64, v33, s8
	v_mul_u32_u24_e32 v0, 0x880, v0
	v_readlane_b32 s8, v247, 45
	v_lshl_add_u64 v[94:95], s[26:27], 0, v[64:65]
	v_lshlrev_b32_e32 v64, 1, v0
	v_readlane_b32 s9, v247, 46
	v_mul_u32_u24_e32 v0, 0x2200, v101
	v_or_b32_e32 v30, v101, v34
	v_lshl_add_u64 v[28:29], s[8:9], 0, v[64:65]
	v_lshlrev_b32_e32 v64, 1, v0
	v_lshl_add_u64 v[0:1], v[94:95], 0, v[64:65]
	v_lshlrev_b32_e32 v64, 1, v2
	v_lshl_add_u64 v[0:1], v[0:1], 0, v[64:65]
	v_lshlrev_b32_e32 v4, 4, v40
	v_mov_b32_e32 v5, v65
	v_lshl_add_u64 v[6:7], v[0:1], 0, v[4:5]
	s_mov_b32 s8, 0x19a000
	v_mul_u32_u24_e32 v8, 0x2200, v30
	v_add_co_u32_e32 v0, vcc, s8, v6
	v_lshlrev_b32_e32 v8, 1, v8
	v_mov_b32_e32 v9, v65
	v_addc_co_u32_e32 v1, vcc, 0, v7, vcc
	v_lshl_add_u64 v[8:9], v[94:95], 0, v[8:9]
	v_mov_b32_e32 v87, v65
	global_load_dwordx4 v[0:3], v[0:1], off offset:512
	v_lshl_add_u64 v[8:9], v[8:9], 0, v[86:87]
	v_lshl_add_u64 v[4:5], v[8:9], 0, v[4:5]
	s_movk_i32 s8, 0x1000
	v_add_co_u32_e32 v8, vcc, s8, v4
	s_mov_b64 s[8:9], 0x19a200
	s_nop 0
	v_addc_co_u32_e32 v9, vcc, 0, v5, vcc
	global_load_dwordx4 v[48:51], v[8:9], off offset:3584
	v_lshl_add_u64 v[6:7], v[6:7], 0, s[8:9]
	global_load_dwordx4 v[16:19], v[6:7], off offset:32
	s_mov_b64 s[8:9], 0x1e00
	v_lshl_add_u64 v[4:5], v[4:5], 0, s[8:9]
	global_load_dwordx4 v[52:55], v[4:5], off offset:32
	global_load_dwordx4 v[20:23], v[6:7], off offset:64
	global_load_dwordx4 v[56:59], v[4:5], off offset:64
	global_load_dwordx4 v[24:27], v[6:7], off offset:96
	global_load_dwordx4 v[60:63], v[4:5], off offset:96
	global_load_dword v31, v[84:85], off
	v_mov_b32_e32 v93, v65
	v_lshl_add_u64 v[96:97], v[28:29], 0, v[92:93]
	global_load_dwordx2 v[32:33], v[96:97], off offset:224
	global_load_dwordx2 v[34:35], v[96:97], off offset:240
	global_load_dwordx2 v[44:45], v[96:97], off offset:192
	global_load_dwordx2 v[46:47], v[96:97], off offset:208
	s_mov_b32 s8, 0x22000
	v_add_co_u32_e32 v28, vcc, s8, v96
	v_and_b32_e32 v70, 64, v162
	s_nop 0
	v_addc_co_u32_e32 v29, vcc, 0, v97, vcc
	global_load_dwordx2 v[36:37], v[28:29], off offset:224
	global_load_dwordx2 v[38:39], v[28:29], off offset:240
	global_load_dwordx2 v[66:67], v[28:29], off offset:192
	global_load_dwordx2 v[68:69], v[28:29], off offset:208
	v_xor_b32_e32 v43, 32, v162
	v_or_b32_e32 v71, 0x70, v90
	v_or_b32_e32 v72, 0x71, v90
	v_or_b32_e32 v73, 0x72, v90
	v_or_b32_e32 v74, 0x73, v90
	v_or_b32_e32 v75, 0x78, v90
	v_or_b32_e32 v76, 0x79, v90
	s_mov_b32 s8, 0xff800000
	s_waitcnt vmcnt(15)
	v_mfma_f32_32x32x16_bf16 v[0:15], v[0:3], v[48:51], 0
	s_waitcnt vmcnt(13)
	v_mfma_f32_32x32x16_bf16 v[0:15], v[16:19], v[52:55], v[0:15]
	v_add_u32_e32 v18, 64, v70
	v_cmp_lt_i32_e32 vcc, v43, v18
	v_or_b32_e32 v16, 0x7a, v90
	v_or_b32_e32 v17, 0x7b, v90
	v_cndmask_b32_e32 v18, v162, v43, vcc
	v_cmp_ge_u32_e32 vcc, v30, v71
	v_lshlrev_b32_e32 v93, 2, v18
	s_waitcnt vmcnt(11)
	v_mfma_f32_32x32x16_bf16 v[0:15], v[20:23], v[56:59], v[0:15]
	s_waitcnt vmcnt(9)
	v_mfma_f32_32x32x16_bf16 v[0:15], v[24:27], v[60:63], v[0:15]
	s_nop 11
	v_cndmask_b32_e32 v0, v165, v8, vcc
	v_cmp_ge_u32_e32 vcc, v30, v72
	s_nop 1
	v_cndmask_b32_e32 v1, v165, v9, vcc
	v_cmp_ge_u32_e32 vcc, v30, v73
	v_max3_f32 v8, v0, s8, v1
	s_mov_b32 s8, 0x3fb8aa3b
	v_cndmask_b32_e32 v2, v165, v10, vcc
	v_cmp_ge_u32_e32 vcc, v30, v74
	s_waitcnt vmcnt(8)
	v_mul_f32_e32 v10, 0x3fb8aa3b, v31
	v_cndmask_b32_e32 v3, v165, v11, vcc
	v_cmp_ge_u32_e32 vcc, v30, v75
	v_max3_f32 v8, v8, v2, v3
	s_nop 0
	v_cndmask_b32_e32 v4, v165, v12, vcc
	v_cmp_ge_u32_e32 vcc, v30, v76
	s_nop 1
	v_cndmask_b32_e32 v5, v165, v13, vcc
	v_cmp_ge_u32_e32 vcc, v30, v16
	v_max3_f32 v8, v8, v4, v5
	s_nop 0
	v_cndmask_b32_e32 v6, v165, v14, vcc
	v_cmp_ge_u32_e32 vcc, v30, v17
	s_nop 1
	v_cndmask_b32_e32 v7, v165, v15, vcc
	v_max3_f32 v8, v8, v6, v7
	ds_bpermute_b32 v9, v93, v8
	v_cmp_ne_u32_e32 vcc, -5, v41
	s_waitcnt lgkmcnt(0)
; #define MFMA32(a, b, c) __builtin_amdgcn_mfma_f32_32x32x16_bf16((a), (b), (c), 0, 0, 0)
; DEVINL unsigned cvt_pk_bf16(float lo, float hi) { const f32x2 v = {lo, hi}; return __builtin_bit_cast(unsigned, __builtin_convertvector(v, bf16x2v)); }
; DEVINL float fexp2(float x) { return __builtin_amdgcn_exp2f(x); }
; DEVINL void swa_task(const Ctx& c, int layer, int b, int qh, int qg) {
;     ...
;     const int kt_lo = (qg - 4) > 4 ? (qg - 4) : 4;
;     const int ntiles = 1 + (qg >= 4 ? (qg - kt_lo + 1) : 0);
;     bf16x8 kfn[4], vfn[2][2];
;     ...
;     SWA_LOAD(3);
;     for (int it = 0; it < ntiles; ++it) {
;         const bool meta = (it == 0);
;         const int kt = meta ? 3 : (kt_lo + it - 1);
;         const int k0 = kt * 32;
;         bf16x8 kf[4], vf[2][2];
; #pragma unroll
;         for (int s = 0; s < 4; ++s) kf[s] = kfn[s];
; #pragma unroll
;         for (int d = 0; d < 2; ++d)
; #pragma unroll
;             for (int s = 0; s < 2; ++s) vf[d][s] = vfn[d][s];
;         { const int nk = (it + 1 < ntiles) ? (kt_lo + it) : kt; SWA_LOAD(nk); }
;     ...
;         tmax = fmaxf(tmax, __shfl_xor(tmax, 32));
;         const float mnew = fmaxf(mrun, tmax);
;         const float alpha = fexp2(mrun - mnew);
;         float psum = 0.f; float pv[16];
; #pragma unroll
;         for (int i = 0; i < 16; ++i) { pv[i] = fexp2(sc[i] - mnew); psum += pv[i]; }
;         psum += __shfl_xor(psum, 32);
;         lrun = lrun * alpha + psum; mrun = mnew;
; #pragma unroll
;         for (int d = 0; d < 2; ++d)
; #pragma unroll
;             for (int i = 0; i < 16; ++i) o[d][i] *= alpha;
; #pragma unroll
;         for (int s = 0; s < 2; ++s) {
;             u32x4 pk;
; #pragma unroll
;             for (int jj = 0; jj < 4; ++jj) pk[jj] = cvt_pk_bf16(pv[8 * s + 2 * jj], pv[8 * s + 2 * jj + 1]);
;             const bf16x8 pf = __builtin_bit_cast(bf16x8, pk);
;             o[0] = MFMA32(vf[0][s], pf, o[0]);
;             o[1] = MFMA32(vf[1][s], pf, o[1]);
;         }
	v_max3_f32 v122, v10, v8, v9
	v_fma_f32 v8, v31, s8, -v122
	v_sub_f32_e32 v9, 0xff800000, v122
	v_exp_f32_e32 v77, v9
	v_exp_f32_e32 v79, v8
	v_sub_f32_e32 v0, v0, v122
	v_sub_f32_e32 v1, v1, v122
	v_sub_f32_e32 v2, v2, v122
	v_sub_f32_e32 v3, v3, v122
	v_exp_f32_e32 v78, v0
	v_mul_f32_e32 v0, 0, v79
	v_cvt_pk_bf16_f32 v70, v77, v77
	v_sub_f32_e32 v43, v4, v122
	v_sub_f32_e32 v74, v5, v122
	v_sub_f32_e32 v75, v6, v122
	v_sub_f32_e32 v76, v7, v122
	v_exp_f32_e32 v80, v1
	v_exp_f32_e32 v81, v2
	v_exp_f32_e32 v87, v3
	v_mov_b32_e32 v71, v70
	v_mov_b32_e32 v72, v70
	v_mov_b32_e32 v73, v70
	v_mov_b32_e32 v1, v0
	v_mov_b32_e32 v2, v0
	v_mov_b32_e32 v3, v0
	v_mov_b32_e32 v4, v0
	v_mov_b32_e32 v5, v0
	v_mov_b32_e32 v6, v0
	v_mov_b32_e32 v7, v0
	v_mov_b32_e32 v8, v0
	v_mov_b32_e32 v9, v0
	v_mov_b32_e32 v10, v0
	v_mov_b32_e32 v11, v0
	v_mov_b32_e32 v12, v0
	v_mov_b32_e32 v13, v0
	v_mov_b32_e32 v14, v0
	v_mov_b32_e32 v15, v0
	v_exp_f32_e32 v43, v43
	s_waitcnt vmcnt(4)
	v_mfma_f32_32x32x16_bf16 v[16:31], v[44:47], v[70:73], v[0:15]
	v_add_f32_e32 v44, 0, v77
	v_add_f32_e32 v44, v77, v44
	v_add_f32_e32 v44, v77, v44
	v_add_f32_e32 v44, v77, v44
	v_add_f32_e32 v44, v77, v44
	v_add_f32_e32 v44, v77, v44
	v_add_f32_e32 v44, v77, v44
	s_waitcnt vmcnt(0)
	v_mfma_f32_32x32x16_bf16 v[0:15], v[66:69], v[70:73], v[0:15]
	v_add_f32_e32 v44, v77, v44
	v_add_f32_e32 v44, v78, v44
	v_exp_f32_e32 v46, v74
	v_add_f32_e32 v44, v80, v44
	v_exp_f32_e32 v47, v75
	v_exp_f32_e32 v74, v76
	v_add_f32_e32 v44, v81, v44
	v_add_f32_e32 v44, v87, v44
	v_add_f32_e32 v44, v43, v44
	v_add_f32_e32 v44, v46, v44
	v_add_f32_e32 v66, v47, v44
	v_cvt_pk_bf16_f32 v44, v78, v80
	v_cvt_pk_bf16_f32 v45, v81, v87
	v_cvt_pk_bf16_f32 v46, v43, v46
	v_cvt_pk_bf16_f32 v47, v47, v74
	s_nop 1
	v_mfma_f32_32x32x16_bf16 v[16:31], v[32:35], v[44:47], v[16:31]
	v_add_f32_e32 v32, v74, v66
	ds_bpermute_b32 v33, v93, v32
	s_waitcnt lgkmcnt(0)
	v_add_f32_e32 v32, v32, v33
	v_mfma_f32_32x32x16_bf16 v[0:15], v[36:39], v[44:47], v[0:15]
	v_add_f32_e32 v32, v79, v32
	s_and_saveexec_b64 s[8:9], vcc
	s_cbranch_execz .LBB0_251
	v_lshl_add_u32 v34, v42, 5, v166
	v_mov_b32_e32 v35, v65
	v_lshl_add_u64 v[36:37], v[34:35], 1, v[96:97]
	v_add_co_u32_e32 v38, vcc, 0x22000, v36
	v_lshrrev_b32_e32 v35, 6, v169
	s_nop 0
	v_addc_co_u32_e32 v39, vcc, 0, v37, vcc
	global_load_dwordx2 v[66:67], v[38:39], off offset:32
	global_load_dwordx2 v[68:69], v[38:39], off offset:48
	global_load_dwordx2 v[70:71], v[38:39], off
	global_load_dwordx2 v[72:73], v[38:39], off offset:16
	global_load_dwordx2 v[74:75], v[36:37], off offset:32
	global_load_dwordx2 v[76:77], v[36:37], off offset:48
	global_load_dwordx2 v[78:79], v[36:37], off
	global_load_dwordx2 v[80:81], v[36:37], off offset:16
	v_sub_u32_e32 v36, 0x43, v35
	v_max_u32_e32 v118, 8, v36
	v_lshlrev_b32_e32 v36, 5, v118
	v_or_b32_e32 v100, v101, v34
	v_sub_u32_e32 v34, v101, v90
	v_lshlrev_b32_e32 v37, 5, v35
	v_add_u32_e32 v35, v118, v35
	v_sub_u32_e32 v34, v34, v36
	v_lshlrev_b32_e32 v33, 3, v40
	v_sub_u32_e32 v35, 0x48, v35
	v_sub_u32_e32 v34, v34, v37
	v_max_i32_e32 v119, 1, v35
	s_mov_b32 s13, 0
	v_mov_b32_e32 v87, v65
	v_add_u32_e32 v120, 5, v41
	v_add_u32_e32 v121, 0x8c5, v34
	s_mov_b64 s[10:11], 0
	v_lshlrev_b32_e32 v98, 1, v33
	s_mov_b32 s16, 0x22000
	s_mov_b32 s17, 0xff800000
	v_mad_u64_u32 v[196:197], s[100:101], v100, s49, v[94:95]
	v_mov_b32_e32 v198, v197
	v_mad_u64_u32 v[198:199], s[100:101], v87, s49, v[198:199]
	v_mov_b32_e32 v197, v198
	v_lshl_add_u64 v[196:197], v[196:197], 0, v[64:65]
	v_mov_b32_e32 v198, v98
	v_mov_b32_e32 v199, v65
	v_lshl_add_u64 v[196:197], v[196:197], 0, v[198:199]
	s_mov_b64 s[100:101], 0x2200
	v_lshl_add_u64 v[196:197], v[196:197], 0, s[100:101]
	global_load_dwordx4 v[180:183], v[196:197], off
	global_load_dwordx4 v[184:187], v[196:197], off offset:32
	global_load_dwordx4 v[188:191], v[196:197], off offset:64
	global_load_dwordx4 v[192:195], v[196:197], off offset:96
.LBB0_249:
	v_mov_b32_e32 v123, v32
	v_mov_b32_e32 v99, v65
	s_add_i32 s12, s13, 1
	v_cmp_lt_i32_e32 vcc, s12, v120
	v_add_u32_e32 v36, s13, v118
	v_add_u32_e32 v99, 27, v121
	v_cndmask_b32_e64 v37, -4, -3, vcc
	v_add_lshl_u32 v36, v36, v37, 5
	v_ashrrev_i32_e32 v37, 31, v36
	v_or_b32_e32 v100, v36, v101
	v_lshl_add_u64 v[36:37], v[36:37], 1, v[96:97]
	global_load_dwordx2 v[104:105], v[36:37], off
	global_load_dwordx2 v[102:103], v[36:37], off offset:16
	global_load_dwordx2 v[108:109], v[36:37], off offset:32
	global_load_dwordx2 v[106:107], v[36:37], off offset:48
	v_add_co_u32_e32 v36, vcc, s16, v36
	v_ashrrev_i32_e32 v87, 31, v100
	s_nop 0
	v_addc_co_u32_e32 v37, vcc, 0, v37, vcc
	global_load_dwordx2 v[112:113], v[36:37], off
	global_load_dwordx2 v[110:111], v[36:37], off offset:16
	global_load_dwordx2 v[116:117], v[36:37], off offset:32
	global_load_dwordx2 v[114:115], v[36:37], off offset:48
	v_cmp_gt_u32_e32 vcc, s39, v99
	v_cvt_f32_i32_e32 v99, v99
	s_mov_b32 s13, s12
	s_waitcnt vmcnt(11)
	v_mfma_f32_32x32x16_bf16 v[32:47], v[180:183], v[48:51], 0
	s_waitcnt vmcnt(10)
	v_mfma_f32_32x32x16_bf16 v[32:47], v[184:187], v[52:55], v[32:47]
	v_add_u32_e32 v124, 25, v121
	s_waitcnt vmcnt(9)
	v_mfma_f32_32x32x16_bf16 v[32:47], v[188:191], v[56:59], v[32:47]
	s_waitcnt vmcnt(8)
; #define MFMA32(a, b, c) __builtin_amdgcn_mfma_f32_32x32x16_bf16((a), (b), (c), 0, 0, 0)
; DEVINL void swa_task(const Ctx& c, int layer, int b, int qh, int qg) {
;     ...
;         f32x16 st;
; #pragma unroll
;         for (int i = 0; i < 16; ++i) st[i] = 0.f;
; #pragma unroll
;         for (int s = 0; s < 4; ++s) st = MFMA32(kf[s], qf[s], st);
;         float sc[16]; float tmax = -INFINITY;
; #pragma unroll
;         for (int i = 0; i < 16; ++i) {
;             const int key = k0 + (i & 3) + 8 * (i >> 2) + 4 * h;
;             const int dist = qpos - key;
;             const bool ok = meta ? (key >= 112 && dist >= 0) : (dist >= 0 && dist < 128);
;             const float v = meta ? st[i] : st[i] - slope2 * (float)dist;
;             sc[i] = ok ? v : -INFINITY;
;             tmax = fmaxf(tmax, sc[i]);
;         }
;         tmax = fmaxf(tmax, __shfl_xor(tmax, 32));
	v_mfma_f32_32x32x16_bf16 v[32:47], v[192:195], v[60:63], v[32:47]
	v_mad_u64_u32 v[196:197], s[100:101], v100, s49, v[94:95]
	v_mov_b32_e32 v198, v197
	v_mad_u64_u32 v[198:199], s[100:101], v87, s49, v[198:199]
	v_mov_b32_e32 v197, v198
	v_lshl_add_u64 v[196:197], v[196:197], 0, v[64:65]
	v_mov_b32_e32 v198, v98
	v_mov_b32_e32 v199, v65
	v_lshl_add_u64 v[196:197], v[196:197], 0, v[198:199]
	s_mov_b64 s[100:101], 0x2200
	v_lshl_add_u64 v[196:197], v[196:197], 0, s[100:101]
	global_load_dwordx4 v[180:183], v[196:197], off
	global_load_dwordx4 v[184:187], v[196:197], off offset:32
	global_load_dwordx4 v[188:191], v[196:197], off offset:64
	global_load_dwordx4 v[192:195], v[196:197], off offset:96
	s_nop 11
	v_fma_f32 v32, -v170, v99, v32
	v_add_u32_e32 v99, 26, v121
	v_cndmask_b32_e32 v32, v165, v32, vcc
	v_cmp_gt_u32_e32 vcc, s39, v99
	v_cvt_f32_i32_e32 v99, v99
	v_fma_f32 v33, -v170, v99, v33
	v_cndmask_b32_e32 v99, v165, v33, vcc
	v_cmp_gt_u32_e32 vcc, s39, v124
	v_cvt_f32_i32_e32 v124, v124
	v_max3_f32 v33, v32, s17, v99
	v_fma_f32 v34, -v170, v124, v34
	v_add_u32_e32 v124, 24, v121
	v_cndmask_b32_e32 v34, v165, v34, vcc
	v_cmp_gt_u32_e32 vcc, s39, v124
	v_cvt_f32_i32_e32 v124, v124
	v_fma_f32 v35, -v170, v124, v35
	v_add_u32_e32 v124, 19, v121
	v_cndmask_b32_e32 v35, v165, v35, vcc
	v_cmp_gt_u32_e32 vcc, s39, v124
	v_cvt_f32_i32_e32 v124, v124
	v_max3_f32 v33, v33, v34, v35
	v_fma_f32 v36, -v170, v124, v36
	v_add_u32_e32 v124, 18, v121
	v_cndmask_b32_e32 v36, v165, v36, vcc
	v_cmp_gt_u32_e32 vcc, s39, v124
	v_cvt_f32_i32_e32 v124, v124
	v_fma_f32 v37, -v170, v124, v37
	v_add_u32_e32 v124, 17, v121
	v_cndmask_b32_e32 v37, v165, v37, vcc
	v_cmp_gt_u32_e32 vcc, s39, v124
	v_cvt_f32_i32_e32 v124, v124
	v_max3_f32 v33, v33, v36, v37
	v_fma_f32 v38, -v170, v124, v38
	v_add_u32_e32 v124, 16, v121
	v_cndmask_b32_e32 v38, v165, v38, vcc
	v_cmp_gt_u32_e32 vcc, s39, v124
	v_cvt_f32_i32_e32 v124, v124
	v_fma_f32 v39, -v170, v124, v39
	v_add_u32_e32 v124, 11, v121
	v_cndmask_b32_e32 v39, v165, v39, vcc
	v_cmp_gt_u32_e32 vcc, s39, v124
	v_cvt_f32_i32_e32 v124, v124
	v_max3_f32 v33, v33, v38, v39
	v_fma_f32 v40, -v170, v124, v40
	v_add_u32_e32 v124, 10, v121
	v_cndmask_b32_e32 v40, v165, v40, vcc
	v_cmp_gt_u32_e32 vcc, s39, v124
	v_cvt_f32_i32_e32 v124, v124
	v_fma_f32 v41, -v170, v124, v41
	v_add_u32_e32 v124, 9, v121
	v_cndmask_b32_e32 v41, v165, v41, vcc
	v_cmp_gt_u32_e32 vcc, s39, v124
	v_cvt_f32_i32_e32 v124, v124
	v_max3_f32 v33, v33, v40, v41
	v_fma_f32 v42, -v170, v124, v42
	v_add_u32_e32 v124, 8, v121
	v_cndmask_b32_e32 v42, v165, v42, vcc
	v_cmp_gt_u32_e32 vcc, s39, v124
	v_cvt_f32_i32_e32 v124, v124
	v_fma_f32 v43, -v170, v124, v43
	v_add_u32_e32 v124, 3, v121
	v_cndmask_b32_e32 v43, v165, v43, vcc
	v_cmp_gt_u32_e32 vcc, s39, v124
	v_cvt_f32_i32_e32 v124, v124
	v_max3_f32 v33, v33, v42, v43
	v_fma_f32 v44, -v170, v124, v44
	v_add_u32_e32 v124, 2, v121
	v_cndmask_b32_e32 v44, v165, v44, vcc
	v_cmp_gt_u32_e32 vcc, s39, v124
	v_cvt_f32_i32_e32 v124, v124
	v_fma_f32 v45, -v170, v124, v45
	v_add_u32_e32 v124, 1, v121
	v_cndmask_b32_e32 v45, v165, v45, vcc
	v_cmp_gt_u32_e32 vcc, s39, v124
	v_cvt_f32_i32_e32 v124, v124
	v_max3_f32 v33, v33, v44, v45
	v_fma_f32 v46, -v170, v124, v46
	v_cvt_f32_i32_e32 v124, v121
	v_cndmask_b32_e32 v46, v165, v46, vcc
	v_cmp_gt_u32_e32 vcc, s39, v121
	v_subrev_u32_e32 v121, 32, v121
	v_fma_f32 v47, -v170, v124, v47
	v_cndmask_b32_e32 v47, v165, v47, vcc
	v_max3_f32 v33, v33, v46, v47
	ds_bpermute_b32 v124, v93, v33
	v_cmp_eq_u32_e32 vcc, s12, v119
	s_or_b64 s[10:11], vcc, s[10:11]
	s_waitcnt lgkmcnt(0)
; #define MFMA32(a, b, c) __builtin_amdgcn_mfma_f32_32x32x16_bf16((a), (b), (c), 0, 0, 0)
; DEVINL unsigned cvt_pk_bf16(float lo, float hi) { const f32x2 v = {lo, hi}; return __builtin_bit_cast(unsigned, __builtin_convertvector(v, bf16x2v)); }
; DEVINL float fexp2(float x) { return __builtin_amdgcn_exp2f(x); }
; DEVINL void swa_task(const Ctx& c, int layer, int b, int qh, int qg) {
;     ...
;         const float mnew = fmaxf(mrun, tmax);
;         const float alpha = fexp2(mrun - mnew);
;         float psum = 0.f; float pv[16];
; #pragma unroll
;         for (int i = 0; i < 16; ++i) { pv[i] = fexp2(sc[i] - mnew); psum += pv[i]; }
;         psum += __shfl_xor(psum, 32);
;         lrun = lrun * alpha + psum; mrun = mnew;
; #pragma unroll
;         for (int d = 0; d < 2; ++d)
; #pragma unroll
;             for (int i = 0; i < 16; ++i) o[d][i] *= alpha;
; #pragma unroll
;         for (int s = 0; s < 2; ++s) {
;             u32x4 pk;
; #pragma unroll
;             for (int jj = 0; jj < 4; ++jj) pk[jj] = cvt_pk_bf16(pv[8 * s + 2 * jj], pv[8 * s + 2 * jj + 1]);
;             const bf16x8 pf = __builtin_bit_cast(bf16x8, pk);
;             o[0] = MFMA32(vf[0][s], pf, o[0]);
;             o[1] = MFMA32(vf[1][s], pf, o[1]);
;         }
	v_max3_f32 v33, v122, v33, v124
	v_sub_f32_e32 v32, v32, v33
	v_exp_f32_e32 v124, v32
	v_sub_f32_e32 v99, v99, v33
	v_exp_f32_e32 v99, v99
	v_sub_f32_e32 v34, v34, v33
	v_exp_f32_e32 v125, v34
	v_sub_f32_e32 v34, v35, v33
	v_exp_f32_e32 v35, v34
	v_sub_f32_e32 v34, v36, v33
	v_add_f32_e32 v32, 0, v124
	v_exp_f32_e32 v36, v34
	v_sub_f32_e32 v34, v37, v33
	v_add_f32_e32 v32, v99, v32
	v_exp_f32_e32 v37, v34
	v_sub_f32_e32 v34, v38, v33
	v_add_f32_e32 v32, v125, v32
	v_exp_f32_e32 v126, v34
	v_sub_f32_e32 v34, v39, v33
	v_add_f32_e32 v32, v35, v32
	v_exp_f32_e32 v39, v34
	v_sub_f32_e32 v34, v40, v33
	v_add_f32_e32 v32, v36, v32
	v_exp_f32_e32 v40, v34
	v_sub_f32_e32 v34, v41, v33
	v_add_f32_e32 v32, v37, v32
	v_exp_f32_e32 v41, v34
	v_sub_f32_e32 v34, v42, v33
	v_add_f32_e32 v32, v126, v32
	v_exp_f32_e32 v42, v34
	v_sub_f32_e32 v34, v43, v33
	v_add_f32_e32 v32, v39, v32
	v_exp_f32_e32 v43, v34
	v_sub_f32_e32 v34, v44, v33
	v_add_f32_e32 v32, v40, v32
	v_exp_f32_e32 v44, v34
	v_sub_f32_e32 v34, v45, v33
	v_add_f32_e32 v32, v41, v32
	v_exp_f32_e32 v45, v34
	v_sub_f32_e32 v34, v46, v33
	v_add_f32_e32 v32, v42, v32
	v_exp_f32_e32 v46, v34
	v_sub_f32_e32 v34, v47, v33
	v_add_f32_e32 v32, v43, v32
	v_exp_f32_e32 v47, v34
	v_add_f32_e32 v32, v44, v32
	v_add_f32_e32 v32, v45, v32
	v_add_f32_e32 v32, v46, v32
	v_add_f32_e32 v32, v47, v32
	v_sub_f32_e32 v122, v122, v33
	ds_bpermute_b32 v34, v93, v32
	v_exp_f32_e32 v38, v122
	v_cvt_pk_bf16_f32 v35, v125, v35
	v_cvt_pk_bf16_f32 v36, v36, v37
	v_cvt_pk_bf16_f32 v37, v126, v39
	v_pk_mul_f32 v[18:19], v[18:19], v[38:39] op_sel_hi:[1,0]
	v_pk_mul_f32 v[20:21], v[20:21], v[38:39] op_sel_hi:[1,0]
	v_pk_mul_f32 v[22:23], v[22:23], v[38:39] op_sel_hi:[1,0]
	v_pk_mul_f32 v[24:25], v[24:25], v[38:39] op_sel_hi:[1,0]
	v_pk_mul_f32 v[26:27], v[26:27], v[38:39] op_sel_hi:[1,0]
	v_pk_mul_f32 v[28:29], v[28:29], v[38:39] op_sel_hi:[1,0]
	v_pk_mul_f32 v[30:31], v[30:31], v[38:39] op_sel_hi:[1,0]
	s_waitcnt lgkmcnt(0)
	v_add_f32_e32 v32, v32, v34
	v_cvt_pk_bf16_f32 v34, v124, v99
	v_pk_mul_f32 v[16:17], v[16:17], v[38:39] op_sel_hi:[1,0]
	v_pk_mul_f32 v[14:15], v[14:15], v[38:39] op_sel_hi:[1,0]
	v_pk_mul_f32 v[12:13], v[12:13], v[38:39] op_sel_hi:[1,0]
	v_pk_mul_f32 v[10:11], v[10:11], v[38:39] op_sel_hi:[1,0]
	v_pk_mul_f32 v[8:9], v[8:9], v[38:39] op_sel_hi:[1,0]
	v_pk_mul_f32 v[6:7], v[6:7], v[38:39] op_sel_hi:[1,0]
	v_pk_mul_f32 v[4:5], v[4:5], v[38:39] op_sel_hi:[1,0]
	v_pk_mul_f32 v[2:3], v[2:3], v[38:39] op_sel_hi:[1,0]
	v_pk_mul_f32 v[0:1], v[0:1], v[38:39] op_sel_hi:[1,0]
	v_mfma_f32_32x32x16_bf16 v[16:31], v[78:81], v[34:37], v[16:31]
	v_fmac_f32_e32 v32, v123, v38
	v_mov_b32_e32 v122, v33
	s_waitcnt vmcnt(11)
	v_mov_b32_e32 v78, v104
	v_mov_b32_e32 v79, v105
	s_waitcnt vmcnt(10)
	v_mov_b32_e32 v80, v102
	v_mov_b32_e32 v81, v103
	v_mfma_f32_32x32x16_bf16 v[0:15], v[70:73], v[34:37], v[0:15]
	v_cvt_pk_bf16_f32 v34, v40, v41
	v_cvt_pk_bf16_f32 v35, v42, v43
	v_cvt_pk_bf16_f32 v36, v44, v45
	v_cvt_pk_bf16_f32 v37, v46, v47
	s_waitcnt vmcnt(7)
	v_mov_b32_e32 v70, v112
	v_mov_b32_e32 v71, v113
	s_waitcnt vmcnt(6)
	v_mov_b32_e32 v72, v110
	v_mfma_f32_32x32x16_bf16 v[16:31], v[74:77], v[34:37], v[16:31]
	v_mov_b32_e32 v73, v111
	v_mov_b32_e32 v74, v108
	v_mov_b32_e32 v75, v109
	v_mov_b32_e32 v76, v106
	v_mov_b32_e32 v77, v107
	v_mfma_f32_32x32x16_bf16 v[0:15], v[66:69], v[34:37], v[0:15]
	s_waitcnt vmcnt(5)
	v_mov_b32_e32 v66, v116
	v_mov_b32_e32 v67, v117
	s_waitcnt vmcnt(4)
	v_mov_b32_e32 v68, v114
	v_mov_b32_e32 v69, v115
	s_andn2_b64 exec, exec, s[10:11]
	s_cbranch_execnz .LBB0_249
	s_or_b64 exec, exec, s[10:11]

; #define MFMA32(a, b, c) __builtin_amdgcn_mfma_f32_32x32x16_bf16((a), (b), (c), 0, 0, 0)
;     DEVINL bf16_t* Z() const { return (bf16_t*)(ws + OFF_Z); }
;     DEVINL bf16_t* AVT() const { return (bf16_t*)(ws + OFF_AVT); }
; DEVINL float fexp2(float x) { return __builtin_amdgcn_exp2f(x); }
; DEVINL float flog2(float x) { return __builtin_amdgcn_logf(x); }
; DEVINL void sb_task(const Ctx& c, int b, int hd, int qg) {
;     ...
;     if (qg < 3) {
;         u32x2 z = {0u, 0u};
; #pragma unroll
;         for (int d = 0; d < 2; ++d)
; #pragma unroll
;             for (int g = 0; g < 4; ++g) *(u32x2*)(yp + d * 32 + 8 * g + 4 * h) = z;
;         return;
;     }
;     const bf16_t* zb = c.Z() + (size_t)b * L * ZW;
;     bf16x8 qf[4];
;     {
;         const bf16_t* qp = zb + (size_t)(q0 + r) * ZW + Z_AQ + hd * 64 + 8 * h;
; #pragma unroll
;         for (int s = 0; s < 4; ++s) qf[s] = *(const bf16x8*)(qp + 16 * s);
;     }
;     f32x16 o[2];
; #pragma unroll
;     for (int d = 0; d < 2; ++d)
; #pragma unroll
;         for (int i = 0; i < 16; ++i) o[d][i] = 0.f;
;     float carry = 0.f;
;     const int qpos = q0 + r;
;     const bf16_t* vtb = c.AVT() + (size_t)(b * 512 + hd * 64 + r) * L + 4 * h;
;     bf16x8 kfn[4], vfn[2][2], kfm[4], vfm[2][2];
;     ...
;     SB_LOAD(kfn, vfn, qg);
;     SB_LOAD(kfm, vfm, (qg > 3 ? qg - 1 : 3));
;     ...
;         f32x16 st;
; #pragma unroll
;         for (int i = 0; i < 16; ++i) st[i] = 0.f;
; #pragma unroll
;         for (int s = 0; s < 4; ++s) st = MFMA32(kf[s], qf[s], st);
;         const bool boundary = (kt == qg) || (kt == 3);
;         float x[16], ls[16];
; #pragma unroll
;         for (int i = 0; i < 16; ++i) {
;             const float z = st[i];
;             const float sp = fmaxf(z, 0.f) + flog2(1.f + fexp2(-fabsf(z)));
;             const int key = k0 + (i & 3) + 8 * (i >> 2) + 4 * h;
;             const bool ok = !boundary || (key < qpos && key >= 112);
;             x[i] = ok ? -sp : 0.f;
;             ls[i] = ok ? z - sp : -INFINITY;
;         }
.LBB0_256:
	s_andn2_saveexec_b64 s[52:53], s[0:1]
	s_cbranch_execz .LBB0_243
	v_ashrrev_i32_e32 v0, 31, v168
	v_lshrrev_b32_e32 v0, 26, v0
	v_add_u32_e32 v0, v168, v0
	v_ashrrev_i32_e32 v0, 6, v0
	v_sub_u32_e32 v172, 0x43, v0
	v_mov_b32_e32 v0, v160
	v_lshlrev_b32_e32 v44, 5, v172
	s_movk_i32 s0, 0x880
	v_mad_u32_u24 v1, v33, s0, v44
	v_and_b32_e32 v87, 31, v0
	v_or_b32_e32 v64, v87, v1
	v_lshlrev_b64 v[2:3], 10, v[64:65]
	v_lshlrev_b32_e32 v1, 6, v168
	v_lshl_add_u64 v[4:5], s[86:87], 0, v[2:3]
	v_and_b32_e32 v2, 0x1c0, v1
	v_bfe_u32 v0, v0, 5, 1
	v_lshlrev_b32_e32 v64, 1, v2
	v_lshl_add_u64 v[88:89], v[4:5], 0, v[64:65]
	v_cmp_lt_u32_e32 vcc, 2, v172
	v_lshlrev_b32_e32 v40, 3, v0
	v_lshlrev_b32_e32 v90, 2, v0
	s_and_saveexec_b64 s[0:1], vcc
	s_xor_b64 s[56:57], exec, s[0:1]
	s_cbranch_execz .LBB0_263
	v_lshlrev_b32_e32 v1, 9, v33
	s_mov_b32 s0, 0x2420000
	v_or3_b32 v1, v1, v2, v87
	v_mul_lo_u32 v4, v33, s0
	v_mul_u32_u24_e32 v1, 0x880, v1
	v_readlane_b32 s0, v247, 47
	v_lshlrev_b32_e32 v2, 1, v1
	v_mov_b32_e32 v3, v65
	v_readlane_b32 s1, v247, 48
	v_mov_b32_e32 v41, v65
	v_mov_b32_e32 v5, v65
	v_lshl_add_u64 v[2:3], s[0:1], 0, v[2:3]
	v_lshl_add_u64 v[92:93], v[2:3], 0, v[40:41]
	v_lshlrev_b32_e32 v2, 1, v44
	v_mov_b32_e32 v3, v65
	v_lshl_add_u64 v[2:3], v[92:93], 0, v[2:3]
	s_mov_b32 s0, 0x22000
	v_lshl_add_u64 v[42:43], s[26:27], 0, v[4:5]
	v_add_co_u32_e32 v4, vcc, s0, v2
	v_or_b32_e32 v45, v87, v44
	s_nop 0
	v_addc_co_u32_e32 v5, vcc, 0, v3, vcc
	global_load_dwordx2 v[32:33], v[4:5], off offset:32
	global_load_dwordx2 v[34:35], v[4:5], off offset:48
	global_load_dwordx2 v[16:17], v[4:5], off
	global_load_dwordx2 v[18:19], v[4:5], off offset:16
	global_load_dwordx2 v[36:37], v[2:3], off offset:32
	global_load_dwordx2 v[38:39], v[2:3], off offset:48
	global_load_dwordx2 v[20:21], v[2:3], off
	global_load_dwordx2 v[22:23], v[2:3], off offset:16
	v_mad_u64_u32 v[2:3], s[0:1], v45, s49, v[42:43]
	v_lshl_add_u64 v[2:3], v[2:3], 0, v[64:65]
	v_lshlrev_b32_e32 v4, 4, v0
	v_mov_b32_e32 v5, v65
	v_lshl_add_u64 v[6:7], v[2:3], 0, v[4:5]
	global_load_dwordx4 v[24:27], v[6:7], off offset:1120
	global_load_dwordx4 v[28:31], v[6:7], off offset:1088
	global_load_dwordx4 v[66:69], v[6:7], off offset:1056
	global_load_dwordx4 v[2:5], v[6:7], off offset:1024
	global_load_dwordx4 v[48:51], v[6:7], off offset:96
	global_load_dwordx4 v[52:55], v[6:7], off offset:64
	global_load_dwordx4 v[56:59], v[6:7], off offset:32
	global_load_dwordx4 v[60:63], v[6:7], off
	v_and_b32_e32 v6, 64, v162
	v_xor_b32_e32 v1, 32, v162
	v_add_u32_e32 v6, 64, v6
	v_cmp_lt_i32_e32 vcc, v1, v6
	v_cmp_eq_u32_e64 s[38:39], 0, v0
	v_cmp_lt_u32_e64 s[0:1], v90, v87
	v_cndmask_b32_e32 v1, v162, v1, vcc
	v_lshlrev_b32_e32 v171, 2, v1
	v_cmp_ne_u32_e32 vcc, 3, v172
	s_and_b64 s[0:1], vcc, s[0:1]
	v_or_b32_e32 v79, 16, v44
	v_or_b32_e32 v81, 24, v44
	s_movk_i32 s20, 0x6f
	v_cmp_lt_u32_e64 s[6:7], s20, v79
	v_or_b32_e32 v95, 17, v44
	v_or_b32_e32 v96, 25, v44
	v_or_b32_e32 v97, 18, v44
	v_cmp_lt_u32_e64 s[8:9], s20, v81
	v_cmp_lt_u32_e64 s[10:11], s20, v95
	v_or_b32_e32 v98, 26, v44
	v_cmp_lt_u32_e64 s[12:13], s20, v96
	v_cmp_lt_u32_e64 s[14:15], s20, v97
	v_or_b32_e32 v99, 19, v44
	v_or_b32_e32 v100, 27, v44
	v_cmp_lt_u32_e64 s[18:19], s20, v99
	v_cmp_lt_u32_e64 s[16:17], s20, v98
	v_cmp_lt_u32_e64 s[20:21], s20, v100
	v_mov_b32_e32 v91, v65
	s_waitcnt vmcnt(0)
	v_mfma_f32_32x32x16_bf16 v[0:15], v[2:5], v[60:63], 0
	v_mfma_f32_32x32x16_bf16 v[0:15], v[66:69], v[56:59], v[0:15]
	v_mfma_f32_32x32x16_bf16 v[0:15], v[28:31], v[52:55], v[0:15]
	v_mfma_f32_32x32x16_bf16 v[0:15], v[24:27], v[48:51], v[0:15]
	s_nop 11
	v_exp_f32_e64 v25, -|v0|
	v_max_f32_e32 v24, v0, v0
	v_max_f32_e32 v24, 0, v24
	v_exp_f32_e64 v27, -|v2|
	v_add_f32_e32 v25, 1.0, v25
	v_log_f32_e32 v25, v25
	v_exp_f32_e64 v28, -|v3|
	v_add_f32_e32 v27, 1.0, v27
	v_log_f32_e32 v27, v27
	v_add_f32_e32 v24, v24, v25
	v_exp_f32_e64 v25, -|v1|
	v_sub_f32_e32 v0, v0, v24
	v_cndmask_b32_e64 v29, 0, -v24, s[0:1]
	v_cndmask_b32_e64 v24, v165, v0, s[0:1]
	v_add_f32_e32 v25, 1.0, v25
	v_log_f32_e32 v25, v25
	v_max_f32_e32 v0, v1, v1
	v_max_f32_e32 v0, 0, v0
	v_add_f32_e32 v28, 1.0, v28
	v_add_f32_e32 v26, v0, v25
	v_or_b32_e32 v0, v90, v44
	v_or_b32_e32 v25, 1, v0
	v_cmp_lt_u32_e64 s[0:1], v25, v45
	s_and_b64 s[0:1], vcc, s[0:1]
	v_sub_f32_e32 v1, v1, v26
	v_cndmask_b32_e64 v25, 0, -v26, s[0:1]
	v_cndmask_b32_e64 v26, v165, v1, s[0:1]
	v_max_f32_e32 v1, v2, v2
	v_max_f32_e32 v1, 0, v1
	v_add_f32_e32 v1, v1, v27
	v_or_b32_e32 v27, 2, v0
	v_cmp_lt_u32_e64 s[0:1], v27, v45
	s_and_b64 s[0:1], vcc, s[0:1]
	v_log_f32_e32 v28, v28
	v_cndmask_b32_e64 v27, 0, -v1, s[0:1]
	v_sub_f32_e32 v1, v2, v1
	v_exp_f32_e64 v30, -|v4|
	v_cndmask_b32_e64 v2, v165, v1, s[0:1]
	v_max_f32_e32 v1, v3, v3
	v_max_f32_e32 v1, 0, v1
	v_add_f32_e32 v1, v1, v28
	v_or_b32_e32 v28, 3, v0
	v_cmp_lt_u32_e64 s[0:1], v28, v45
	v_add_f32_e32 v30, 1.0, v30
	s_and_b64 s[0:1], vcc, s[0:1]
	v_log_f32_e32 v30, v30
	v_cndmask_b32_e64 v28, 0, -v1, s[0:1]
	v_sub_f32_e32 v1, v3, v1
	v_cndmask_b32_e64 v3, v165, v1, s[0:1]
	v_max_f32_e32 v1, v4, v4
	v_max_f32_e32 v1, 0, v1
	v_add_f32_e32 v1, v1, v30
	v_or_b32_e32 v30, 8, v0
	v_cmp_lt_u32_e64 s[0:1], v30, v45
	v_exp_f32_e64 v30, -|v5|
	s_and_b64 s[0:1], vcc, s[0:1]
	v_cndmask_b32_e64 v41, 0, -v1, s[0:1]
	v_sub_f32_e32 v1, v4, v1
	v_add_f32_e32 v30, 1.0, v30
	v_log_f32_e32 v30, v30
	v_exp_f32_e64 v31, -|v6|
	v_cndmask_b32_e64 v4, v165, v1, s[0:1]
	v_max_f32_e32 v1, v5, v5
	v_max_f32_e32 v1, 0, v1
	v_add_f32_e32 v1, v1, v30
	v_or_b32_e32 v30, 9, v0
	v_cmp_lt_u32_e64 s[0:1], v30, v45
	v_add_f32_e32 v31, 1.0, v31
	s_and_b64 s[0:1], vcc, s[0:1]
; #define MFMA32(a, b, c) __builtin_amdgcn_mfma_f32_32x32x16_bf16((a), (b), (c), 0, 0, 0)
; DEVINL unsigned cvt_pk_bf16(float lo, float hi) { const f32x2 v = {lo, hi}; return __builtin_bit_cast(unsigned, __builtin_convertvector(v, bf16x2v)); }
; DEVINL float fexp2(float x) { return __builtin_amdgcn_exp2f(x); }
; DEVINL float flog2(float x) { return __builtin_amdgcn_logf(x); }
; DEVINL void sb_task(const Ctx& c, int b, int hd, int qg) {
;     ...
;         const bool boundary = (kt == qg) || (kt == 3);
;         float x[16], ls[16];
; #pragma unroll
;         for (int i = 0; i < 16; ++i) {
;             const float z = st[i];
;             const float sp = fmaxf(z, 0.f) + flog2(1.f + fexp2(-fabsf(z)));
;             const int key = k0 + (i & 3) + 8 * (i >> 2) + 4 * h;
;             const bool ok = !boundary || (key < qpos && key >= 112);
;             x[i] = ok ? -sp : 0.f;
;             ls[i] = ok ? z - sp : -INFINITY;
;         }
;         float og[4], tot[4];
; #pragma unroll
;         for (int g = 0; g < 4; ++g) {
;             const float gs = (x[4 * g] + x[4 * g + 1]) + (x[4 * g + 2] + x[4 * g + 3]);
;             og[g] = __shfl_xor(gs, 32);
;             tot[g] = gs + og[g];
;         }
;         float suf[4];
;         suf[3] = 0.f; suf[2] = tot[3]; suf[1] = suf[2] + tot[2]; suf[0] = suf[1] + tot[1];
;         float a[16];
; #pragma unroll
;         for (int g = 0; g < 4; ++g) {
;             float af = carry + suf[g] + (h == 0 ? og[g] : 0.f);
;             a[4 * g + 3] = fexp2(ls[4 * g + 3] + af); af += x[4 * g + 3];
;             a[4 * g + 2] = fexp2(ls[4 * g + 2] + af); af += x[4 * g + 2];
;             a[4 * g + 1] = fexp2(ls[4 * g + 1] + af); af += x[4 * g + 1];
;             a[4 * g + 0] = fexp2(ls[4 * g + 0] + af);
;         }
;         carry += (tot[0] + tot[1]) + (tot[2] + tot[3]);
;         const bool sb_done = __all(carry < -80.f);
; #pragma unroll
;         for (int s = 0; s < 2; ++s) {
;             u32x4 pk;
; #pragma unroll
;             for (int jj = 0; jj < 4; ++jj) pk[jj] = cvt_pk_bf16(a[8 * s + 2 * jj], a[8 * s + 2 * jj + 1]);
;             const bf16x8 pf = __builtin_bit_cast(bf16x8, pk);
;             o[0] = MFMA32(vf[0][s], pf, o[0]);
;             o[1] = MFMA32(vf[1][s], pf, o[1]);
;         }
;         if (sb_done) break;
	v_log_f32_e32 v31, v31
	v_cndmask_b32_e64 v30, 0, -v1, s[0:1]
	v_sub_f32_e32 v1, v5, v1
	v_exp_f32_e64 v46, -|v7|
	v_cndmask_b32_e64 v5, v165, v1, s[0:1]
	v_max_f32_e32 v1, v6, v6
	v_max_f32_e32 v1, 0, v1
	v_add_f32_e32 v1, v1, v31
	v_or_b32_e32 v31, 10, v0
	v_cmp_lt_u32_e64 s[0:1], v31, v45
	v_add_f32_e32 v46, 1.0, v46
	s_and_b64 s[0:1], vcc, s[0:1]
	v_log_f32_e32 v46, v46
	v_cndmask_b32_e64 v31, 0, -v1, s[0:1]
	v_sub_f32_e32 v1, v6, v1
	v_cndmask_b32_e64 v6, v165, v1, s[0:1]
	v_max_f32_e32 v1, v7, v7
	v_max_f32_e32 v1, 0, v1
	v_or_b32_e32 v0, 11, v0
	v_add_f32_e32 v1, v1, v46
	v_cmp_lt_u32_e64 s[0:1], v0, v45
	s_and_b64 s[0:1], vcc, s[0:1]
	v_sub_f32_e32 v0, v7, v1
	v_cndmask_b32_e64 v7, v165, v0, s[0:1]
	v_max_f32_e32 v0, v8, v8
	v_cndmask_b32_e64 v94, 0, -v1, s[0:1]
	v_max_f32_e32 v1, 0, v0
	v_exp_f32_e64 v0, -|v8|
	v_exp_f32_e64 v46, -|v12|
	v_exp_f32_e64 v68, -|v13|
	v_exp_f32_e64 v72, -|v14|
	v_add_f32_e32 v0, 1.0, v0
	v_log_f32_e32 v47, v0
	v_max_f32_e32 v0, v9, v9
	v_max_f32_e32 v67, 0, v0
	v_exp_f32_e64 v0, -|v9|
	v_add_f32_e32 v46, 1.0, v46
	v_log_f32_e32 v46, v46
	v_add_f32_e32 v68, 1.0, v68
	v_add_f32_e32 v0, 1.0, v0
	v_log_f32_e32 v69, v0
	v_max_f32_e32 v0, v10, v10
	v_max_f32_e32 v71, 0, v0
	v_exp_f32_e64 v0, -|v10|
	v_log_f32_e32 v68, v68
	v_exp_f32_e64 v76, -|v15|
	v_add_f32_e32 v29, v29, v25
	v_add_f32_e32 v0, 1.0, v0
	v_log_f32_e32 v73, v0
	v_max_f32_e32 v0, v11, v11
	v_max_f32_e32 v75, 0, v0
	v_exp_f32_e64 v0, -|v11|
	v_add_f32_e32 v78, v27, v28
	v_add_f32_e32 v29, v29, v78
	v_add_f32_e32 v41, v41, v30
	v_add_f32_e32 v0, 1.0, v0
	v_log_f32_e32 v77, v0
	v_max_f32_e32 v0, v12, v12
	v_add_f32_e32 v78, v31, v94
	v_max_f32_e32 v0, 0, v0
	v_max_f32_e32 v66, v13, v13
	v_add_f32_e32 v78, v41, v78
	v_or_b32_e32 v41, v90, v79
	v_max_f32_e32 v66, 0, v66
	v_add_f32_e32 v72, 1.0, v72
	v_pk_add_f32 v[0:1], v[0:1], v[46:47]
	v_or_b32_e32 v46, v90, v81
	v_cmp_lt_u32_e64 s[0:1], v41, v45
	v_log_f32_e32 v72, v72
	v_add_f32_e32 v76, 1.0, v76
	v_sub_f32_e32 v8, v8, v1
	v_cmp_lt_u32_e64 s[4:5], v46, v45
	s_and_b64 s[0:1], s[6:7], s[0:1]
	v_pk_add_f32 v[46:47], v[66:67], v[68:69]
	v_log_f32_e32 v76, v76
	v_cndmask_b32_e64 v41, v165, v8, s[0:1]
	v_sub_f32_e32 v8, v9, v47
	v_or_b32_e32 v9, v90, v95
	v_max_f32_e32 v70, v14, v14
	v_or_b32_e32 v66, v90, v96
	v_cmp_lt_u32_e64 s[6:7], v9, v45
	v_max_f32_e32 v70, 0, v70
	v_max_f32_e32 v74, v15, v15
	s_and_b64 s[4:5], s[8:9], s[4:5]
	v_cmp_lt_u32_e64 s[8:9], v66, v45
	s_and_b64 s[6:7], s[10:11], s[6:7]
	v_or_b32_e32 v66, v90, v97
	v_max_f32_e32 v74, 0, v74
	v_cndmask_b32_e64 v68, v165, v8, s[6:7]
	v_pk_add_f32 v[8:9], v[70:71], v[72:73]
	v_or_b32_e32 v67, v90, v98
	v_cmp_lt_u32_e64 s[10:11], v66, v45
	s_and_b64 s[8:9], s[12:13], s[8:9]
	v_sub_f32_e32 v10, v10, v9
	v_cmp_lt_u32_e64 s[12:13], v67, v45
	s_and_b64 s[10:11], s[14:15], s[10:11]
	v_pk_add_f32 v[66:67], v[74:75], v[76:77]
	v_cndmask_b32_e64 v69, v165, v10, s[10:11]
	v_sub_f32_e32 v10, v11, v67
	v_or_b32_e32 v11, v90, v99
	v_cmp_lt_u32_e64 s[14:15], v11, v45
	v_or_b32_e32 v70, v90, v100
	s_and_b64 s[14:15], s[18:19], s[14:15]
	s_and_b64 s[12:13], s[16:17], s[12:13]
	v_cmp_lt_u32_e64 s[16:17], v70, v45
	v_cndmask_b32_e64 v70, v165, v10, s[14:15]
	v_cndmask_b32_e64 v10, 0, -v0, s[4:5]
	v_sub_f32_e32 v0, v12, v0
	v_sub_f32_e32 v12, v13, v46
	s_and_b64 s[16:17], s[20:21], s[16:17]
	v_cndmask_b32_e64 v72, v165, v12, s[8:9]
	v_cndmask_b32_e64 v12, 0, -v8, s[12:13]
	v_sub_f32_e32 v8, v14, v8
	v_cndmask_b32_e64 v11, 0, -v1, s[0:1]
	v_cndmask_b32_e64 v71, v165, v0, s[4:5]
	v_cndmask_b32_e64 v1, 0, -v47, s[6:7]
	v_cndmask_b32_e64 v0, 0, -v46, s[8:9]
	v_cndmask_b32_e64 v13, 0, -v9, s[10:11]
	v_cndmask_b32_e64 v73, v165, v8, s[12:13]
	v_cndmask_b32_e64 v9, 0, -v67, s[14:15]
	v_cndmask_b32_e64 v8, 0, -v66, s[16:17]
	v_sub_f32_e32 v14, v15, v66
	v_cndmask_b32_e64 v66, v165, v14, s[16:17]
	v_pk_add_f32 v[10:11], v[10:11], v[0:1]
	v_pk_add_f32 v[14:15], v[12:13], v[8:9]
	ds_bpermute_b32 v80, v171, v78
	v_pk_add_f32 v[10:11], v[10:11], v[14:15]
	ds_bpermute_b32 v15, v171, v11
	ds_bpermute_b32 v14, v171, v10
	ds_bpermute_b32 v101, v171, v29
	s_mov_b32 s0, 0xc2a00000
	s_waitcnt lgkmcnt(1)
	v_pk_add_f32 v[10:11], v[10:11], v[14:15]
	s_nop 0
	v_mov_b32_e32 v79, v10
	v_mov_b32_e32 v81, v11
	v_pk_add_f32 v[46:47], v[78:79], v[80:81]
	s_waitcnt lgkmcnt(0)
	v_cndmask_b32_e64 v67, 0, v101, s[38:39]
	v_add_f32_e32 v11, v46, v47
	v_add_f32_e32 v11, 0, v11
	v_add_f32_e32 v11, v67, v11
	v_add_f32_e32 v3, v3, v11
	v_add_f32_e32 v11, v28, v11
	v_add_f32_e32 v2, v2, v11
	v_add_f32_e32 v11, v27, v11
	v_add_f32_e32 v10, 0, v10
	v_cndmask_b32_e64 v15, 0, v15, s[38:39]
	v_add_f32_e32 v26, v26, v11
	v_add_f32_e32 v11, v25, v11
	v_add_f32_e32 v10, v15, v10
	v_add_f32_e32 v11, v24, v11
	v_add_f32_e32 v24, 0, v47
	v_cndmask_b32_e64 v25, 0, v80, s[38:39]
	v_add_f32_e32 v9, v9, v10
	v_add_f32_e32 v24, v25, v24
	v_add_f32_e32 v15, v70, v10
	v_add_f32_e32 v10, v69, v9
	v_add_f32_e32 v9, v13, v9
	v_add_f32_e32 v7, v7, v24
	v_add_f32_e32 v24, v94, v24
	v_add_f32_e32 v1, v1, v9
	v_add_f32_e32 v6, v6, v24
	v_add_f32_e32 v24, v31, v24
	v_add_f32_e32 v1, v41, v1
	v_add_f32_e32 v5, v5, v24
	v_add_f32_e32 v24, v30, v24
	v_exp_f32_e32 v70, v1
	v_add_f32_e32 v1, 0, v14
	v_add_f32_e32 v4, v4, v24
	v_cndmask_b32_e64 v1, 0, v1, s[38:39]
	v_exp_f32_e32 v3, v3
	v_exp_f32_e32 v2, v2
	v_exp_f32_e32 v26, v26
	v_exp_f32_e32 v11, v11
	v_exp_f32_e32 v7, v7
	v_exp_f32_e32 v6, v6
	v_exp_f32_e32 v5, v5
	v_exp_f32_e32 v4, v4
	v_exp_f32_e32 v69, v10
	v_add_f32_e32 v10, v68, v9
	v_add_f32_e32 v9, v1, v66
	v_add_f32_e32 v1, v8, v1
	v_add_f32_e32 v8, v1, v73
	v_add_f32_e32 v1, v12, v1
	v_add_f32_e32 v0, v0, v1
	v_add_f32_e32 v29, v29, v101
	v_add_f32_e32 v0, v71, v0
	v_exp_f32_e32 v73, v8
	v_add_f32_e32 v8, v72, v1
	v_exp_f32_e32 v71, v0
	v_add_f32_e32 v0, v46, v29
	v_cvt_pk_bf16_f32 v24, v11, v26
	v_cvt_pk_bf16_f32 v25, v2, v3
	v_cvt_pk_bf16_f32 v26, v4, v5
	v_cvt_pk_bf16_f32 v27, v6, v7
	v_exp_f32_e32 v67, v15
	v_exp_f32_e32 v68, v10
	v_exp_f32_e32 v74, v9
	v_exp_f32_e32 v72, v8
	v_add_f32_e32 v41, v47, v0
	v_mfma_f32_32x32x16_bf16 v[0:15], v[20:23], v[24:27], 0
	v_cvt_pk_bf16_f32 v66, v70, v68
	v_cvt_pk_bf16_f32 v67, v69, v67
	v_cvt_pk_bf16_f32 v68, v71, v72
	v_cvt_pk_bf16_f32 v69, v73, v74
	v_cmp_gt_f32_e64 s[0:1], s0, v41
	s_cmp_lg_u64 s[0:1], exec
	s_cselect_b64 s[0:1], -1, 0
	v_mfma_f32_32x32x16_bf16 v[16:31], v[16:19], v[24:27], 0
	s_and_b64 s[0:1], vcc, s[0:1]
	v_mfma_f32_32x32x16_bf16 v[0:15], v[36:39], v[66:69], v[0:15]
	v_mfma_f32_32x32x16_bf16 v[16:31], v[32:35], v[66:69], v[16:31]
	s_and_saveexec_b64 s[60:61], s[0:1]
	s_cbranch_execz .LBB0_262
; #define MFMA32(a, b, c) __builtin_amdgcn_mfma_f32_32x32x16_bf16((a), (b), (c), 0, 0, 0)
; DEVINL void sb_task(const Ctx& c, int b, int hd, int qg) {
;     ...
;     SB_LOAD(kfn, vfn, qg);
;     SB_LOAD(kfm, vfm, (qg > 3 ? qg - 1 : 3));
;     ...
;         const int k0 = kt * 32;
;         bf16x8 kf[4], vf[2][2];
; #pragma unroll
;         for (int s = 0; s < 4; ++s) { kf[s] = kfn[s]; kfn[s] = kfm[s]; }
; #pragma unroll
;         for (int d = 0; d < 2; ++d)
; #pragma unroll
;             for (int s = 0; s < 2; ++s) { vf[d][s] = vfn[d][s]; vfn[d][s] = vfm[d][s]; }
;         SB_LOAD(kfm, vfm, (kt > 4 ? kt - 2 : 3));
;         f32x16 st;
; #pragma unroll
;         for (int i = 0; i < 16; ++i) st[i] = 0.f;
; #pragma unroll
;         for (int s = 0; s < 4; ++s) st = MFMA32(kf[s], qf[s], st);
	v_max_u32_e32 v32, 5, v172
	v_lshl_add_u32 v32, v32, 5, v167
	v_mov_b32_e32 v33, v65
	v_lshl_add_u64 v[34:35], v[32:33], 1, v[92:93]
	v_add_co_u32_e32 v36, vcc, 0x22000, v34
	s_mov_b32 s66, 0x22000
	s_nop 0
	v_addc_co_u32_e32 v37, vcc, 0, v35, vcc
	global_load_dwordx2 v[124:125], v[36:37], off offset:32
	global_load_dwordx2 v[126:127], v[36:37], off offset:48
	global_load_dwordx2 v[94:95], v[36:37], off
	global_load_dwordx2 v[96:97], v[36:37], off offset:16
	global_load_dwordx2 v[98:99], v[34:35], off offset:32
	global_load_dwordx2 v[100:101], v[34:35], off offset:48
	global_load_dwordx2 v[102:103], v[34:35], off
	global_load_dwordx2 v[104:105], v[34:35], off offset:16
	v_subrev_u32_e32 v34, 32, v44
	v_mov_b32_e32 v35, v65
	v_lshl_add_u64 v[36:37], v[34:35], 1, v[92:93]
	v_add_co_u32_e32 v38, vcc, s66, v36
	v_or_b32_e32 v33, 0x70, v90
	s_nop 0
	v_addc_co_u32_e32 v39, vcc, 0, v37, vcc
	global_load_dwordx2 v[66:67], v[38:39], off offset:32
	global_load_dwordx2 v[68:69], v[38:39], off offset:48
	global_load_dwordx2 v[70:71], v[38:39], off
	global_load_dwordx2 v[72:73], v[38:39], off offset:16
	global_load_dwordx2 v[74:75], v[36:37], off offset:32
	global_load_dwordx2 v[76:77], v[36:37], off offset:48
	global_load_dwordx2 v[78:79], v[36:37], off
	global_load_dwordx2 v[80:81], v[36:37], off offset:16
	v_cmp_lt_u32_e32 vcc, v33, v45
	v_or_b32_e32 v33, 0x71, v90
	v_cmp_lt_u32_e64 s[4:5], v33, v45
	v_or_b32_e32 v33, 0x72, v90
	v_cmp_lt_u32_e64 s[6:7], v33, v45
	v_or_b32_e32 v33, 0x73, v90
	v_cmp_lt_u32_e64 s[8:9], v33, v45
	v_or_b32_e32 v33, 0x78, v90
	v_cmp_lt_u32_e64 s[10:11], v33, v45
	v_or_b32_e32 v33, 0x79, v90
	v_cmp_lt_u32_e64 s[12:13], v33, v45
	v_or_b32_e32 v33, 0x7a, v90
	v_or_b32_e32 v174, v87, v34
	v_cmp_lt_u32_e64 s[14:15], v33, v45
	v_or_b32_e32 v33, 0x7b, v90
	v_lshl_add_u64 v[34:35], v[42:43], 0, v[64:65]
	v_lshlrev_b32_e32 v64, 1, v40
	v_add_f32_e32 v173, 0, v41
	v_cmp_lt_u32_e64 s[16:17], v33, v45
	v_lshl_add_u64 v[106:107], v[34:35], 0, v[64:65]
	s_mov_b64 s[54:55], 0
	v_mov_b32_e32 v64, v32
	s_mov_b32 s94, 0xc2a00000
	v_mad_u64_u32 v[196:197], s[100:101], v174, s49, v[106:107]
	global_load_dwordx4 v[180:183], v[196:197], off offset:1024
	global_load_dwordx4 v[184:187], v[196:197], off offset:1056
	global_load_dwordx4 v[188:191], v[196:197], off offset:1088
	global_load_dwordx4 v[192:195], v[196:197], off offset:1120
.LBB0_260:
	v_add_u32_e32 v175, -1, v172
	v_max_u32_e32 v36, 5, v175
	v_or_b32_e32 v174, v64, v87
	v_lshl_add_u32 v64, v36, 5, v167
	v_lshl_add_u64 v[36:37], v[64:65], 1, v[92:93]
	global_load_dwordx2 v[110:111], v[36:37], off
	global_load_dwordx2 v[108:109], v[36:37], off offset:16
	global_load_dwordx2 v[114:115], v[36:37], off offset:32
	global_load_dwordx2 v[112:113], v[36:37], off offset:48
	v_add_co_u32_e64 v36, s[0:1], s66, v36
	v_add_f32_e32 v176, 0, v173
	s_nop 0
	v_addc_co_u32_e64 v37, s[0:1], 0, v37, s[0:1]
	global_load_dwordx2 v[118:119], v[36:37], off
	global_load_dwordx2 v[116:117], v[36:37], off offset:16
	global_load_dwordx2 v[122:123], v[36:37], off offset:32
	global_load_dwordx2 v[120:121], v[36:37], off offset:48
	v_cmp_ne_u32_e64 s[0:1], 4, v172
	s_or_b64 s[18:19], s[0:1], vcc
	s_or_b64 s[28:29], s[0:1], s[10:11]
	s_or_b64 s[20:21], s[0:1], s[4:5]
	s_or_b64 s[24:25], s[0:1], s[6:7]
	s_or_b64 s[30:31], s[0:1], s[12:13]
	s_or_b64 s[34:35], s[0:1], s[14:15]
	s_or_b64 s[26:27], s[0:1], s[8:9]
	s_or_b64 s[36:37], s[0:1], s[16:17]
	s_waitcnt vmcnt(11)
	v_mfma_f32_32x32x16_bf16 v[32:47], v[180:183], v[60:63], 0
	s_waitcnt vmcnt(10)
	v_mfma_f32_32x32x16_bf16 v[32:47], v[184:187], v[56:59], v[32:47]
	s_waitcnt vmcnt(9)
	v_mfma_f32_32x32x16_bf16 v[32:47], v[188:191], v[52:55], v[32:47]
	s_waitcnt vmcnt(8)
	v_mfma_f32_32x32x16_bf16 v[32:47], v[192:195], v[48:51], v[32:47]
	v_mad_u64_u32 v[196:197], s[100:101], v174, s49, v[106:107]
	global_load_dwordx4 v[180:183], v[196:197], off offset:1024
	global_load_dwordx4 v[184:187], v[196:197], off offset:1056
	global_load_dwordx4 v[188:191], v[196:197], off offset:1088
	global_load_dwordx4 v[192:195], v[196:197], off offset:1120
	s_nop 11
	v_max_f32_e32 v128, v32, v32
	v_max_f32_e32 v129, 0, v128
	v_exp_f32_e64 v128, -|v32|
	v_exp_f32_e64 v130, -|v44|
	v_exp_f32_e64 v134, -|v45|
	v_exp_f32_e64 v138, -|v46|
	v_add_f32_e32 v128, 1.0, v128
	v_log_f32_e32 v133, v128
	v_max_f32_e32 v128, v33, v33
	v_max_f32_e32 v131, 0, v128
	v_exp_f32_e64 v128, -|v33|
	v_add_f32_e32 v130, 1.0, v130
	v_exp_f32_e64 v144, -|v47|
	v_log_f32_e32 v132, v130
	v_add_f32_e32 v128, 1.0, v128
	v_log_f32_e32 v137, v128
	v_max_f32_e32 v128, v34, v34
	v_max_f32_e32 v135, 0, v128
	v_exp_f32_e64 v128, -|v34|
	v_add_f32_e32 v134, 1.0, v134
	v_log_f32_e32 v136, v134
	v_add_f32_e32 v138, 1.0, v138
	v_add_f32_e32 v128, 1.0, v128
	v_log_f32_e32 v141, v128
	v_max_f32_e32 v128, v35, v35
	v_max_f32_e32 v139, 0, v128
	v_exp_f32_e64 v128, -|v35|
	v_max_f32_e32 v130, v45, v45
	v_log_f32_e32 v140, v138
	v_add_f32_e32 v144, 1.0, v144
	v_add_f32_e32 v128, 1.0, v128
	v_log_f32_e32 v145, v128
	v_max_f32_e32 v128, v36, v36
	v_max_f32_e32 v143, 0, v128
	v_exp_f32_e64 v128, -|v36|
	v_max_f32_e32 v130, 0, v130
	v_log_f32_e32 v144, v144
	v_max_f32_e32 v134, v46, v46
	v_add_f32_e32 v128, 1.0, v128
	v_log_f32_e32 v149, v128
	v_max_f32_e32 v128, v37, v37
	v_max_f32_e32 v147, 0, v128
	v_exp_f32_e64 v128, -|v37|
	v_pk_add_f32 v[130:131], v[130:131], v[136:137]
	v_max_f32_e32 v134, 0, v134
	v_max_f32_e32 v138, v47, v47
	v_add_f32_e32 v128, 1.0, v128
	v_log_f32_e32 v153, v128
	v_max_f32_e32 v128, v38, v38
	v_max_f32_e32 v151, 0, v128
	v_exp_f32_e64 v128, -|v38|
	v_max_f32_e32 v138, 0, v138
	v_add_f32_e32 v128, 1.0, v128
; #define MFMA32(a, b, c) __builtin_amdgcn_mfma_f32_32x32x16_bf16((a), (b), (c), 0, 0, 0)
; DEVINL unsigned cvt_pk_bf16(float lo, float hi) { const f32x2 v = {lo, hi}; return __builtin_bit_cast(unsigned, __builtin_convertvector(v, bf16x2v)); }
; DEVINL float fexp2(float x) { return __builtin_amdgcn_exp2f(x); }
; DEVINL float flog2(float x) { return __builtin_amdgcn_logf(x); }
; DEVINL void sb_task(const Ctx& c, int b, int hd, int qg) {
;     ...
;         const bool boundary = (kt == qg) || (kt == 3);
;         float x[16], ls[16];
; #pragma unroll
;         for (int i = 0; i < 16; ++i) {
;             const float z = st[i];
;             const float sp = fmaxf(z, 0.f) + flog2(1.f + fexp2(-fabsf(z)));
;             const int key = k0 + (i & 3) + 8 * (i >> 2) + 4 * h;
;             const bool ok = !boundary || (key < qpos && key >= 112);
;             x[i] = ok ? -sp : 0.f;
;             ls[i] = ok ? z - sp : -INFINITY;
;         }
;         float og[4], tot[4];
; #pragma unroll
;         for (int g = 0; g < 4; ++g) {
;             const float gs = (x[4 * g] + x[4 * g + 1]) + (x[4 * g + 2] + x[4 * g + 3]);
;             og[g] = __shfl_xor(gs, 32);
;             tot[g] = gs + og[g];
;         }
;         float suf[4];
;         suf[3] = 0.f; suf[2] = tot[3]; suf[1] = suf[2] + tot[2]; suf[0] = suf[1] + tot[1];
;         float a[16];
; #pragma unroll
;         for (int g = 0; g < 4; ++g) {
;             float af = carry + suf[g] + (h == 0 ? og[g] : 0.f);
;             a[4 * g + 3] = fexp2(ls[4 * g + 3] + af); af += x[4 * g + 3];
;             a[4 * g + 2] = fexp2(ls[4 * g + 2] + af); af += x[4 * g + 2];
;             a[4 * g + 1] = fexp2(ls[4 * g + 1] + af); af += x[4 * g + 1];
;             a[4 * g + 0] = fexp2(ls[4 * g + 0] + af);
;         }
;         carry += (tot[0] + tot[1]) + (tot[2] + tot[3]);
;         const bool sb_done = __all(carry < -80.f);
; #pragma unroll
;         for (int s = 0; s < 2; ++s) {
;             u32x4 pk;
; #pragma unroll
;             for (int jj = 0; jj < 4; ++jj) pk[jj] = cvt_pk_bf16(a[8 * s + 2 * jj], a[8 * s + 2 * jj + 1]);
;             const bf16x8 pf = __builtin_bit_cast(bf16x8, pk);
;             o[0] = MFMA32(vf[0][s], pf, o[0]);
;             o[1] = MFMA32(vf[1][s], pf, o[1]);
;         }
;         if (sb_done) break;
	v_log_f32_e32 v157, v128
	v_max_f32_e32 v128, v39, v39
	v_max_f32_e32 v155, 0, v128
	v_exp_f32_e64 v128, -|v39|
	s_nop 0
	v_add_f32_e32 v128, 1.0, v128
	v_log_f32_e32 v159, v128
	v_max_f32_e32 v128, v40, v40
	v_max_f32_e32 v142, 0, v128
	v_exp_f32_e64 v128, -|v40|
	s_nop 0
	v_add_f32_e32 v128, 1.0, v128
	v_log_f32_e32 v148, v128
	v_max_f32_e32 v128, v41, v41
	v_max_f32_e32 v146, 0, v128
	v_exp_f32_e64 v128, -|v41|
	s_nop 0
	v_add_f32_e32 v128, 1.0, v128
	v_log_f32_e32 v152, v128
	v_max_f32_e32 v128, v42, v42
	v_max_f32_e32 v150, 0, v128
	v_exp_f32_e64 v128, -|v42|
	s_nop 0
	v_add_f32_e32 v128, 1.0, v128
	v_log_f32_e32 v156, v128
	v_max_f32_e32 v128, v43, v43
	v_max_f32_e32 v154, 0, v128
	v_exp_f32_e64 v128, -|v43|
	s_nop 0
	v_add_f32_e32 v128, 1.0, v128
	v_log_f32_e32 v158, v128
	v_max_f32_e32 v128, v44, v44
	v_max_f32_e32 v128, 0, v128
	v_pk_add_f32 v[128:129], v[128:129], v[132:133]
	v_pk_add_f32 v[132:133], v[138:139], v[144:145]
	v_sub_f32_e32 v32, v32, v129
	v_cndmask_b32_e64 v177, v165, v32, s[0:1]
	v_sub_f32_e32 v32, v33, v131
	v_cndmask_b32_e64 v178, v165, v32, s[0:1]
	v_pk_add_f32 v[32:33], v[134:135], v[140:141]
	v_pk_add_f32 v[134:135], v[146:147], v[152:153]
	v_sub_f32_e32 v34, v34, v33
	v_cndmask_b32_e64 v140, v165, v34, s[0:1]
	v_sub_f32_e32 v34, v35, v133
	v_cndmask_b32_e64 v138, v165, v34, s[0:1]
	v_pk_add_f32 v[34:35], v[142:143], v[148:149]
	v_pk_add_f32 v[136:137], v[154:155], v[158:159]
	v_sub_f32_e32 v36, v36, v35
	v_cndmask_b32_e64 v139, v165, v36, s[0:1]
	v_sub_f32_e32 v36, v37, v135
	v_cndmask_b32_e64 v141, v165, v36, s[0:1]
	v_pk_add_f32 v[36:37], v[150:151], v[156:157]
	v_sub_f32_e32 v44, v44, v128
	v_sub_f32_e32 v38, v38, v37
	v_cndmask_b32_e64 v142, v165, v38, s[0:1]
	v_sub_f32_e32 v38, v39, v137
	v_cndmask_b32_e64 v143, v165, v38, s[0:1]
	v_cndmask_b32_e64 v38, 0, -v34, s[18:19]
	v_sub_f32_e32 v34, v40, v34
	v_sub_f32_e32 v40, v41, v134
	v_cndmask_b32_e64 v41, 0, -v37, s[0:1]
	v_cndmask_b32_e64 v37, 0, -v137, s[0:1]
	v_cndmask_b32_e64 v137, v165, v44, s[28:29]
	v_sub_f32_e32 v44, v45, v130
	v_cndmask_b32_e64 v144, v165, v34, s[18:19]
	v_cndmask_b32_e64 v34, 0, -v134, s[20:21]
	v_cndmask_b32_e64 v134, v165, v40, s[20:21]
	v_cndmask_b32_e64 v40, 0, -v36, s[24:25]
	v_sub_f32_e32 v36, v42, v36
	v_sub_f32_e32 v42, v43, v136
	v_cndmask_b32_e64 v145, v165, v44, s[30:31]
	v_cndmask_b32_e64 v44, 0, -v32, s[34:35]
	v_sub_f32_e32 v32, v46, v32
	v_cndmask_b32_e64 v39, 0, -v35, s[0:1]
	v_cndmask_b32_e64 v35, 0, -v135, s[0:1]
	v_cndmask_b32_e64 v135, v165, v36, s[24:25]
	v_cndmask_b32_e64 v36, 0, -v136, s[26:27]
	v_cndmask_b32_e64 v136, v165, v42, s[26:27]
	v_cndmask_b32_e64 v43, 0, -v129, s[0:1]
	v_cndmask_b32_e64 v42, 0, -v128, s[28:29]
	v_cndmask_b32_e64 v129, 0, -v131, s[0:1]
	v_cndmask_b32_e64 v128, 0, -v130, s[30:31]
	v_cndmask_b32_e64 v45, 0, -v33, s[0:1]
	v_cndmask_b32_e64 v146, v165, v32, s[34:35]
	v_cndmask_b32_e64 v33, 0, -v133, s[0:1]
	v_cndmask_b32_e64 v32, 0, -v132, s[36:37]
	v_sub_f32_e32 v46, v47, v132
	v_cndmask_b32_e64 v147, v165, v46, s[36:37]
	v_pk_add_f32 v[42:43], v[42:43], v[128:129]
	v_pk_add_f32 v[46:47], v[44:45], v[32:33]
	v_pk_add_f32 v[38:39], v[38:39], v[34:35]
	v_pk_add_f32 v[130:131], v[40:41], v[36:37]
	v_pk_add_f32 v[42:43], v[42:43], v[46:47]
	v_pk_add_f32 v[38:39], v[38:39], v[130:131]
	ds_bpermute_b32 v47, v171, v43
	ds_bpermute_b32 v131, v171, v39
	ds_bpermute_b32 v130, v171, v38
	ds_bpermute_b32 v46, v171, v42
	s_waitcnt lgkmcnt(1)
	v_pk_add_f32 v[38:39], v[38:39], v[130:131]
	s_waitcnt lgkmcnt(0)
	v_pk_add_f32 v[42:43], v[42:43], v[46:47]
	s_nop 0
	v_pk_add_f32 v[132:133], v[38:39], v[42:43]
	s_nop 0
	v_add_f32_e32 v38, v39, v132
	v_add_f32_e32 v38, v173, v38
	v_cndmask_b32_e64 v39, 0, v47, s[38:39]
	v_add_f32_e32 v38, v39, v38
	v_add_f32_e32 v33, v33, v38
	v_add_f32_e32 v39, v138, v38
	v_add_f32_e32 v38, v140, v33
	v_add_f32_e32 v33, v45, v33
	v_add_f32_e32 v45, v173, v132
	v_cndmask_b32_e64 v47, 0, v131, s[38:39]
	v_add_f32_e32 v45, v47, v45
	v_add_f32_e32 v37, v37, v45
	v_add_f32_e32 v47, v143, v45
	v_add_f32_e32 v45, v142, v37
	v_add_f32_e32 v37, v41, v37
	v_add_f32_e32 v41, v141, v37
	v_add_f32_e32 v35, v35, v37
	v_add_f32_e32 v37, v173, v42
	v_cndmask_b32_e64 v42, 0, v130, s[38:39]
	v_add_f32_e32 v37, v42, v37
	v_add_f32_e32 v36, v36, v37
	v_add_f32_e32 v42, v136, v37
	v_add_f32_e32 v37, v135, v36
	v_add_f32_e32 v36, v40, v36
	v_add_f32_e32 v34, v34, v36
	v_add_f32_e32 v34, v144, v34
	v_add_f32_e32 v40, v134, v36
	v_exp_f32_e32 v36, v34
	v_cndmask_b32_e64 v34, 0, v46, s[38:39]
	v_add_f32_e32 v43, v178, v33
	v_add_f32_e32 v33, v129, v33
	v_add_f32_e32 v34, v176, v34
	v_add_f32_e32 v33, v177, v33
	v_add_f32_e32 v35, v139, v35
	v_add_f32_e32 v32, v32, v34
	v_exp_f32_e32 v39, v39
	v_exp_f32_e32 v38, v38
	v_exp_f32_e32 v43, v43
	v_exp_f32_e32 v33, v33
	v_exp_f32_e32 v47, v47
	v_exp_f32_e32 v45, v45
	v_exp_f32_e32 v41, v41
	v_exp_f32_e32 v35, v35
	v_add_f32_e32 v46, v34, v147
	v_add_f32_e32 v34, v32, v146
	v_add_f32_e32 v32, v44, v32
	v_exp_f32_e32 v129, v34
	v_add_f32_e32 v34, v145, v32
	v_add_f32_e32 v32, v128, v32
	v_add_f32_e32 v32, v137, v32
	v_exp_f32_e32 v128, v32
	v_add_f32_e32 v32, v132, v133
	v_exp_f32_e32 v44, v34
	v_add_f32_e32 v173, v173, v32
	v_cvt_pk_bf16_f32 v32, v33, v43
	v_cvt_pk_bf16_f32 v33, v38, v39
	v_cvt_pk_bf16_f32 v34, v35, v41
	v_cvt_pk_bf16_f32 v35, v45, v47
	v_exp_f32_e32 v42, v42
	v_exp_f32_e32 v37, v37
	v_mfma_f32_32x32x16_bf16 v[0:15], v[78:81], v[32:35], v[0:15]
	v_exp_f32_e32 v40, v40
	v_exp_f32_e32 v46, v46
	v_cmp_gt_f32_e64 s[0:1], s94, v173
	s_cmp_eq_u64 s[0:1], exec
	s_cselect_b64 s[18:19], -1, 0
	v_cmp_gt_u32_e64 s[0:1], 5, v172
	s_or_b64 s[0:1], s[18:19], s[0:1]
	v_mfma_f32_32x32x16_bf16 v[16:31], v[70:73], v[32:35], v[16:31]
	v_cvt_pk_bf16_f32 v32, v36, v40
	v_cvt_pk_bf16_f32 v33, v37, v42
	v_cvt_pk_bf16_f32 v34, v128, v44
	v_cvt_pk_bf16_f32 v35, v129, v46
	s_and_b64 s[0:1], exec, s[0:1]
	s_or_b64 s[54:55], s[0:1], s[54:55]
	v_mov_b32_e32 v172, v175
	v_mfma_f32_32x32x16_bf16 v[0:15], v[74:77], v[32:35], v[0:15]
	v_mov_b32_e32 v70, v94
	v_mov_b32_e32 v71, v95
	v_mov_b32_e32 v72, v96
	v_mov_b32_e32 v73, v97
	v_mov_b32_e32 v74, v98
	v_mov_b32_e32 v75, v99
	v_mov_b32_e32 v76, v100
	v_mfma_f32_32x32x16_bf16 v[16:31], v[66:69], v[32:35], v[16:31]
	v_mov_b32_e32 v66, v124
	v_mov_b32_e32 v67, v125
	v_mov_b32_e32 v68, v126
	v_mov_b32_e32 v69, v127
	v_mov_b32_e32 v77, v101
	v_mov_b32_e32 v78, v102
	v_mov_b32_e32 v79, v103
	v_mov_b32_e32 v80, v104
	v_mov_b32_e32 v81, v105
	s_waitcnt vmcnt(5)
	v_mov_b32_e32 v124, v122
	v_mov_b32_e32 v125, v123
	s_waitcnt vmcnt(4)
	v_mov_b32_e32 v126, v120
	v_mov_b32_e32 v127, v121
	v_mov_b32_e32 v94, v118
	v_mov_b32_e32 v95, v119
	v_mov_b32_e32 v96, v116
	v_mov_b32_e32 v97, v117
	v_mov_b32_e32 v98, v114
	v_mov_b32_e32 v99, v115
	v_mov_b32_e32 v100, v112
	v_mov_b32_e32 v101, v113
	v_mov_b32_e32 v102, v110
	v_mov_b32_e32 v103, v111
	v_mov_b32_e32 v104, v108
	v_mov_b32_e32 v105, v109
	s_andn2_b64 exec, exec, s[54:55]
	s_cbranch_execnz .LBB0_260
; DEVINL void sb_task(const Ctx& c, int b, int hd, int qg) {
;     ...
;         if (sb_done) break;
;     }
; #pragma unroll
	s_or_b64 exec, exec, s[54:55]
	v_readlane_b32 s26, v247, 7
	v_readlane_b32 s27, v247, 8
